# prompt attention: L2-touch prefetch of K/V chunk c+2 (one dword per lane) issued with chunk c+1 LDS-DMA; loop wait vmcnt(0)->vmcnt(1)
# baseline (speedup 1.0000x reference)
.LBB0_483:
	s_and_b64 vcc, exec, s[0:1]
	s_cbranch_vccz .LBB0_598
	s_and_b32 s0, s5, 0xffff
	s_mul_i32 s0, s0, 0xaaab
	s_lshr_b32 s39, s0, 21
	s_mul_i32 s0, s39, 48
	s_sub_i32 s0, s5, s0
	s_and_b32 s1, s0, 0xff
	s_mulk_i32 s1, 0xab
	s_load_dwordx4 s[12:15], s[52:53], 0x80
	s_bfe_u32 s2, s1, 0x5000b
	s_mul_i32 s3, s2, 12
	v_mov_b32_e32 v4, v0
	s_sub_i32 s0, s0, s3
	s_sub_i32 s42, 7, s39
	v_readfirstlane_b32 s40, v4
	s_and_b32 s44, s0, 0xff
	s_ashr_i32 s66, s40, 6
	s_mov_b64 s[6:7], 0
	s_waitcnt lgkmcnt(0)
	s_add_u32 s36, s12, s6
	s_addc_u32 s37, s13, s7
	s_add_u32 s68, s36, 0x4c00000
	v_and_b32_e32 v212, 31, v4
	s_addc_u32 s69, s37, 0
	s_lshl_b32 s41, s42, 8
	s_and_b32 s0, s1, 0xf800
	s_or_b32 s5, s0, s41
	v_lshlrev_b32_e32 v3, 3, v212
	v_or_b32_e32 v5, s5, v3
	v_add_u32_e32 v5, s66, v5
	v_mov_b64_e32 v[6:7], s[68:69]
	v_mad_i64_i32 v[6:7], s[0:1], v5, s19, v[6:7]
	v_bfe_u32 v211, v4, 5, 1
	s_lshl_b32 s0, s44, 8
	s_mov_b32 s1, s21
	v_lshl_add_u64 v[6:7], v[6:7], 0, s[0:1]
	v_lshlrev_b32_e32 v198, 4, v211
	v_mov_b32_e32 v199, v2
	v_lshl_add_u64 v[6:7], v[6:7], 0, v[198:199]
	s_lshl_b32 s43, s66, 2
	v_bfe_u32 v197, v4, 4, 2
	global_load_dwordx4 v[162:165], v[6:7], off
	global_load_dwordx4 v[166:169], v[6:7], off offset:32
	global_load_dwordx4 v[170:173], v[6:7], off offset:64
	global_load_dwordx4 v[174:177], v[6:7], off offset:96
	global_load_dwordx4 v[178:181], v[6:7], off offset:128
	global_load_dwordx4 v[182:185], v[6:7], off offset:160
	global_load_dwordx4 v[186:189], v[6:7], off offset:192
	global_load_dwordx4 v[190:193], v[6:7], off offset:224
	v_or_b32_e32 v5, s43, v197
	v_lshlrev_b32_e32 v6, 4, v4
	v_and_b32_e32 v6, 0xf0, v6
	v_lshlrev_b32_e32 v7, 4, v5
	s_movk_i32 s0, 0x70
	v_bitop3_b32 v6, v7, v6, s0 bitop3:0x6c
	s_ashr_i32 s1, s40, 4
	v_lshrrev_b32_e32 v8, 1, v6
	s_and_b32 s3, s1, 0x3ffffff0
	v_lshrrev_b32_e32 v6, 2, v4
	v_lshrrev_b32_e32 v199, 1, v4
	s_lshr_b32 s1, s1, 1
	s_lshl_b32 s0, s66, 1
	v_and_or_b32 v6, v6, 3, s3
	v_and_b32_e32 v7, 8, v199
	s_and_b32 s1, s1, 4
	s_lshl_b32 s20, s44, 7
	v_or3_b32 v6, v6, v7, s1
	v_and_or_b32 v7, s0, 2, v211
	v_lshlrev_b32_e32 v210, 3, v4
	v_lshlrev_b32_e32 v7, 5, v7
	v_and_b32_e32 v9, 24, v210
	s_add_i32 s0, s20, 0xc00
	s_ashr_i32 s67, s66, 31
	v_lshlrev_b32_e32 v10, 2, v6
	v_or3_b32 v6, v7, v9, s0
	v_mov_b32_e32 v7, v2
	s_movk_i32 s3, 0x1800
	s_mul_i32 s2, s2, 0x1800000
	v_mad_i64_i32 v[200:201], s[0:1], v10, s3, v[6:7]
	s_add_u32 s70, s68, s2
	v_lshlrev_b32_e32 v5, 2, v5
	s_addc_u32 s71, s69, 0
	s_lshl_b32 s0, s66, 10
	v_mov_b64_e32 v[6:7], s[20:21]
	s_add_i32 s38, s0, 0
	v_mad_i64_i32 v[202:203], s[0:1], v5, s3, v[6:7]
	v_or_b32_e32 v202, v202, v8
	v_lshl_add_u64 v[6:7], v[202:203], 1, s[70:71]
	s_mov_b64 s[0:1], 0xc00
	v_lshl_add_u64 v[8:9], v[6:7], 0, s[0:1]
	s_add_i32 s0, s38, 0x8000
	s_mov_b32 m0, s38
	v_lshl_add_u64 v[10:11], v[200:201], 1, s[70:71]
	global_load_lds_dwordx4 v[8:9], off
	s_mov_b32 m0, s0
	s_mov_b64 s[0:1], 0x3c00
	global_load_lds_dwordx4 v[10:11], off
	v_lshl_add_u64 v[8:9], v[6:7], 0, s[0:1]
	s_add_i32 m0, s38, 0x2000
	s_mov_b64 s[0:1], 0x3000
	global_load_lds_dwordx4 v[8:9], off
	v_lshl_add_u64 v[8:9], v[10:11], 0, s[0:1]
	s_add_i32 m0, s38, 0xa000
	s_mov_b64 s[0:1], 0x6c00
	global_load_lds_dwordx4 v[8:9], off
	v_lshl_add_u64 v[8:9], v[6:7], 0, s[0:1]
	s_add_i32 m0, s38, 0x4000
	s_mov_b64 s[0:1], 0x6000
	global_load_lds_dwordx4 v[8:9], off
	v_lshl_add_u64 v[8:9], v[10:11], 0, s[0:1]
	s_add_i32 m0, s38, 0xc000
	s_mov_b64 s[0:1], 0x9c00
	global_load_lds_dwordx4 v[8:9], off
	v_lshl_add_u64 v[6:7], v[6:7], 0, s[0:1]
	s_add_i32 m0, s38, 0x6000
	s_mov_b64 s[0:1], 0x9000
	global_load_lds_dwordx4 v[6:7], off
	v_lshl_add_u64 v[6:7], v[10:11], 0, s[0:1]
	s_add_i32 m0, s38, 0xe000
	s_movk_i32 s0, 0xa80
	global_load_lds_dwordx4 v[6:7], off
	v_lshrrev_b32_e32 v250, 2, v0
	v_bfe_u32 v251, v0, 1, 1
	v_mul_u32_u24_e32 v250, 0x3000, v250
	v_mul_u32_u24_e32 v251, 0xc00, v251
	s_lshl_b32 s2, s20, 1
	v_add_u32_e32 v250, v250, v251
	v_and_b32_e32 v251, 1, v0
	s_addk_i32 s2, 0xc00
	v_lshlrev_b32_e32 v251, 7, v251
	v_add_u32_e32 v250, s2, v250
	v_add_u32_e32 v250, v250, v251
	v_cmp_gt_i32_e32 vcc, s0, v4
	s_and_saveexec_b64 s[0:1], vcc
	s_cbranch_execz .LBB0_497
	v_max_i32_e32 v5, 0x880, v4
	v_sub_u32_e32 v5, v5, v4
	v_add_u32_e32 v5, 0x1ff, v5
	s_movk_i32 s2, 0x1ff
	v_cmp_lt_u32_e32 vcc, s2, v5
	s_mov_b64 s[2:3], -1
	v_mov_b32_e32 v6, v4
	s_and_saveexec_b64 s[12:13], vcc
	s_cbranch_execz .LBB0_494
	s_mul_i32 s2, s44, 0x2a00
	v_lshrrev_b32_e32 v8, 9, v5
	s_add_u32 s2, s36, s2
	s_addc_u32 s3, s37, 0
	v_add_u32_e32 v6, -1, v8
	s_add_u32 s14, s2, 0x2900000
	v_add_u32_e32 v5, 0x200, v4
	v_lshrrev_b32_e32 v7, 1, v6
	s_addc_u32 s15, s3, 0
	v_add_u32_e32 v9, 1, v7
	v_cmp_lt_u32_e32 vcc, 13, v6
	v_mov_b32_e32 v12, 0
	v_mov_b64_e32 v[6:7], v[4:5]
	s_and_saveexec_b64 s[24:25], vcc
	s_cbranch_execz .LBB0_490
	v_and_b32_e32 v10, -8, v9
	v_lshl_add_u32 v11, v4, 2, s51
	s_mov_b32 s2, 0
	s_mov_b64 s[72:73], 0
	v_mov_b64_e32 v[6:7], v[4:5]

.LBB0_499:
	s_mul_i32 s0, s24, 0x180000
	s_mul_hi_u32 s1, s24, 0x180000
	s_add_u32 s0, s70, s0
	s_addc_u32 s1, s71, s1
	s_lshl_b32 s16, s24, 16
	s_and_b32 s16, s16, 0x10000
	s_add_i32 s16, s38, s16
	v_lshl_add_u64 v[4:5], v[202:203], 1, s[0:1]
	s_mov_b64 s[40:41], 0xc00
	v_lshl_add_u64 v[6:7], v[4:5], 0, s[40:41]
	v_lshl_add_u64 v[8:9], v[200:201], 1, s[0:1]
	s_add_i32 s0, s16, 0x8000
	s_mov_b32 m0, s16
	s_nop 0
	global_load_lds_dwordx4 v[6:7], off
	s_mov_b32 m0, s0
	s_mov_b64 s[0:1], 0x3c00
	global_load_lds_dwordx4 v[8:9], off
	v_lshl_add_u64 v[6:7], v[4:5], 0, s[0:1]
	s_add_i32 m0, s16, 0x2000
	s_mov_b64 s[0:1], 0x3000
	global_load_lds_dwordx4 v[6:7], off
	v_lshl_add_u64 v[6:7], v[8:9], 0, s[0:1]
	s_add_i32 m0, s16, 0xa000
	s_mov_b64 s[0:1], 0x6c00
	global_load_lds_dwordx4 v[6:7], off
	v_lshl_add_u64 v[6:7], v[4:5], 0, s[0:1]
	s_add_i32 m0, s16, 0x4000
	s_mov_b64 s[0:1], 0x6000
	global_load_lds_dwordx4 v[6:7], off
	v_lshl_add_u64 v[6:7], v[8:9], 0, s[0:1]
	s_add_i32 m0, s16, 0xc000
	s_mov_b64 s[0:1], 0x9c00
	global_load_lds_dwordx4 v[6:7], off
	v_lshl_add_u64 v[4:5], v[4:5], 0, s[0:1]
	s_add_i32 m0, s16, 0x6000
	s_mov_b64 s[0:1], 0x9000
	global_load_lds_dwordx4 v[4:5], off
	v_lshl_add_u64 v[4:5], v[8:9], 0, s[0:1]
	s_add_i32 m0, s16, 0xe000
	s_nop 0
	global_load_lds_dwordx4 v[4:5], off
	s_add_i32 s0, s24, 1
	s_cmp_ge_u32 s0, s3
	s_cbranch_scc1 .Lpa_nopf
	s_mul_i32 s1, s0, 0x180000
	s_add_u32 s0, s70, s1
	s_addc_u32 s1, s71, 0
	global_load_dword v249, v250, s[0:1]
.Lpa_nopf:
.LBB0_500:
	s_cmp_lt_i32 s25, s12
	s_mov_b64 s[0:1], -1
	s_cbranch_scc1 .LBB0_508
	v_and_b32_e32 v4, 64, v206
	v_xor_b32_e32 v3, 32, v206
	v_add_u32_e32 v4, 64, v4
	v_cmp_lt_i32_e32 vcc, v3, v4
	s_and_b32 s0, s15, 0x10000
	v_mov_b64_e32 v[144:145], v[32:33]
	v_cndmask_b32_e32 v3, v206, v3, vcc
	v_mov_b64_e32 v[128:129], v[48:49]
	v_mov_b64_e32 v[112:113], v[64:65]
	v_mov_b64_e32 v[96:97], v[80:81]
	v_add_u32_e32 v12, s0, v227
	v_or_b32_e32 v13, s0, v228
	v_or_b32_e32 v14, s0, v229
	v_or_b32_e32 v15, s0, v230
	v_or_b32_e32 v16, s0, v231
	v_or_b32_e32 v17, s0, v232
	v_or_b32_e32 v238, s0, v233
	v_or_b32_e32 v239, s0, v234
	v_or_b32_e32 v240, s0, v235
	s_mov_b32 s39, 0
	v_lshlrev_b32_e32 v241, 2, v3
	v_mov_b32_e32 v242, v226
	v_mov_b64_e32 v[142:143], v[30:31]
	v_mov_b64_e32 v[140:141], v[28:29]
	v_mov_b64_e32 v[138:139], v[26:27]
	v_mov_b64_e32 v[136:137], v[24:25]
	v_mov_b64_e32 v[134:135], v[22:23]
	v_mov_b64_e32 v[132:133], v[20:21]
	v_mov_b64_e32 v[130:131], v[18:19]
	v_mov_b64_e32 v[126:127], v[46:47]
	v_mov_b64_e32 v[124:125], v[44:45]
	v_mov_b64_e32 v[122:123], v[42:43]
	v_mov_b64_e32 v[120:121], v[40:41]
	v_mov_b64_e32 v[118:119], v[38:39]
	v_mov_b64_e32 v[116:117], v[36:37]
	v_mov_b64_e32 v[114:115], v[34:35]
	v_mov_b64_e32 v[110:111], v[62:63]
	v_mov_b64_e32 v[108:109], v[60:61]
	v_mov_b64_e32 v[106:107], v[58:59]
	v_mov_b64_e32 v[104:105], v[56:57]
	v_mov_b64_e32 v[102:103], v[54:55]
	v_mov_b64_e32 v[100:101], v[52:53]
	v_mov_b64_e32 v[98:99], v[50:51]
	v_mov_b64_e32 v[94:95], v[78:79]
	v_mov_b64_e32 v[92:93], v[76:77]
	v_mov_b64_e32 v[90:91], v[74:75]
	v_mov_b64_e32 v[88:89], v[72:73]
	v_mov_b64_e32 v[86:87], v[70:71]
	v_mov_b64_e32 v[84:85], v[68:69]
	v_mov_b64_e32 v[82:83], v[66:67]
	v_mov_b32_e32 v243, v236
	v_mov_b32_e32 v3, v237

.LBB0_515:
	s_add_i32 s0, s24, 1
	s_cmp_ge_u32 s0, s3
	s_cbranch_scc1 .Lpa_w0
	s_waitcnt vmcnt(1)
	s_branch .Lpa_wd

.Lpa_wd:
	s_add_i32 s15, s15, 0x10000
	s_cmp_eq_u32 s24, s3
	v_add_u32_e32 v226, 0xfffffe00, v226
	s_waitcnt lgkmcnt(0)
	s_barrier
	s_cbranch_scc0 .LBB0_498
	s_and_saveexec_b64 s[0:1], s[6:7]
	ds_write_b32 v222, v147 offset:128
	s_or_b64 exec, exec, s[0:1]
	s_waitcnt lgkmcnt(0)
	v_lshl_add_u32 v3, v211, 4, s2
	ds_read_b32 v4, v3 offset:128
	s_lshl_b32 s0, s66, 14
	v_lshlrev_b32_e32 v5, 2, v212
	v_lshlrev_b32_e32 v6, 11, v211
	s_add_i32 s0, s0, 0
	s_waitcnt lgkmcnt(0)
	v_rcp_f32_e32 v4, v4
	v_add3_u32 v6, s0, v5, v6
	v_add_u32_e32 v14, 0x3000, v6
	v_or_b32_e32 v48, 64, v213
	v_mul_f32_e32 v5, v130, v4
	v_mul_f32_e32 v7, v114, v4
	ds_write2_b32 v6, v5, v7 offset1:32
	v_mul_f32_e32 v5, v98, v4
	v_mul_f32_e32 v4, v82, v4
	ds_write2_b32 v6, v5, v4 offset0:64 offset1:96
	ds_read_b32 v4, v3 offset:132
	v_or_b32_e32 v49, 0x80, v213
	s_lshl_b32 s20, s20, 1
	v_and_b32_e32 v38, 0x78, v210
	v_mov_b32_e32 v13, v2
	s_waitcnt lgkmcnt(0)
	v_rcp_f32_e32 v4, v4
	v_or_b32_e32 v50, 0x100, v213
	v_or_b32_e32 v51, 0x140, v213
	v_or_b32_e32 v52, 0x180, v213
	v_mul_f32_e32 v5, v131, v4
	v_mul_f32_e32 v7, v115, v4
	v_mul_f32_e32 v8, v99, v4
	v_mul_f32_e32 v4, v83, v4
	ds_write2_b32 v6, v5, v7 offset0:128 offset1:160
	ds_write2_b32 v6, v8, v4 offset0:192 offset1:224
	ds_read_b32 v4, v3 offset:136
	v_add_u32_e32 v5, 0x400, v6
	v_or_b32_e32 v53, 0x1c0, v213
	s_waitcnt lgkmcnt(0)
	v_rcp_f32_e32 v4, v4
	s_nop 0
	v_mul_f32_e32 v7, v132, v4
	v_mul_f32_e32 v8, v116, v4
	v_mul_f32_e32 v9, v100, v4
	v_mul_f32_e32 v4, v84, v4
	ds_write2_b32 v5, v7, v8 offset1:32
	ds_write2_b32 v5, v9, v4 offset0:64 offset1:96
	ds_read_b32 v4, v3 offset:140
	s_waitcnt lgkmcnt(0)
	v_rcp_f32_e32 v4, v4
	s_nop 0
	v_mul_f32_e32 v7, v133, v4
	v_mul_f32_e32 v8, v117, v4
	v_mul_f32_e32 v9, v101, v4
	v_mul_f32_e32 v4, v85, v4
	ds_write2_b32 v5, v7, v8 offset0:128 offset1:160
	ds_write2_b32 v5, v9, v4 offset0:192 offset1:224
	ds_read_b32 v4, v3 offset:160
	v_add_u32_e32 v5, 0x1000, v6
	s_waitcnt lgkmcnt(0)
	v_rcp_f32_e32 v4, v4
	s_nop 0
	v_mul_f32_e32 v7, v134, v4
	v_mul_f32_e32 v8, v118, v4
	v_mul_f32_e32 v9, v102, v4
	v_mul_f32_e32 v4, v86, v4
	ds_write2_b32 v5, v7, v8 offset1:32
	ds_write2_b32 v5, v9, v4 offset0:64 offset1:96
	ds_read_b32 v4, v3 offset:164
	s_waitcnt lgkmcnt(0)
	v_rcp_f32_e32 v4, v4
	s_nop 0
	v_mul_f32_e32 v7, v135, v4
	v_mul_f32_e32 v8, v119, v4
	v_mul_f32_e32 v9, v103, v4
	v_mul_f32_e32 v4, v87, v4
	ds_write2_b32 v5, v7, v8 offset0:128 offset1:160
	ds_write2_b32 v5, v9, v4 offset0:192 offset1:224
	ds_read_b32 v4, v3 offset:168
	v_add_u32_e32 v5, 0x1400, v6
	s_waitcnt lgkmcnt(0)
	v_rcp_f32_e32 v4, v4
	s_nop 0
	v_mul_f32_e32 v7, v136, v4
	v_mul_f32_e32 v8, v120, v4
	v_mul_f32_e32 v9, v104, v4
	v_mul_f32_e32 v4, v88, v4
	ds_write2_b32 v5, v7, v8 offset1:32
	ds_write2_b32 v5, v9, v4 offset0:64 offset1:96
	ds_read_b32 v4, v3 offset:172
	s_waitcnt lgkmcnt(0)
	v_rcp_f32_e32 v4, v4
	s_nop 0
	v_mul_f32_e32 v7, v137, v4
	v_mul_f32_e32 v8, v121, v4
	v_mul_f32_e32 v9, v105, v4
	v_mul_f32_e32 v4, v89, v4
	ds_write2_b32 v5, v7, v8 offset0:128 offset1:160
	ds_write2_b32 v5, v9, v4 offset0:192 offset1:224
	ds_read_b32 v4, v3 offset:192
	v_add_u32_e32 v5, 0x2000, v6
	s_waitcnt lgkmcnt(0)
	v_rcp_f32_e32 v4, v4
	s_nop 0
	v_mul_f32_e32 v7, v138, v4
	v_mul_f32_e32 v8, v122, v4
	v_mul_f32_e32 v9, v106, v4
	v_mul_f32_e32 v4, v90, v4
	ds_write2_b32 v5, v7, v8 offset1:32
	ds_write2_b32 v5, v9, v4 offset0:64 offset1:96
	ds_read_b32 v4, v3 offset:196
	s_waitcnt lgkmcnt(0)
	v_rcp_f32_e32 v4, v4
	s_nop 0
	v_mul_f32_e32 v7, v139, v4
	v_mul_f32_e32 v8, v123, v4
	v_mul_f32_e32 v9, v107, v4
	v_mul_f32_e32 v4, v91, v4
	ds_write2_b32 v5, v7, v8 offset0:128 offset1:160
	ds_write2_b32 v5, v9, v4 offset0:192 offset1:224
	ds_read_b32 v4, v3 offset:200
	v_add_u32_e32 v7, 0x2400, v6
	s_waitcnt lgkmcnt(0)
	v_rcp_f32_e32 v4, v4
	s_nop 0
	v_mul_f32_e32 v5, v140, v4
	v_mul_f32_e32 v8, v124, v4
	v_mul_f32_e32 v9, v108, v4
	v_mul_f32_e32 v4, v92, v4
	ds_write2_b32 v7, v5, v8 offset1:32
	ds_write2_b32 v7, v9, v4 offset0:64 offset1:96
	ds_read_b32 v4, v3 offset:204
	v_and_or_b32 v8, v199, 24, s5
	v_add_u32_e32 v8, s66, v8
	s_waitcnt lgkmcnt(0)
	v_rcp_f32_e32 v9, v4
	v_mov_b64_e32 v[4:5], s[68:69]
	v_mul_f32_e32 v10, v141, v9
	v_mul_f32_e32 v11, v125, v9
	v_mul_f32_e32 v12, v109, v9
	v_mul_f32_e32 v9, v93, v9
	ds_write2_b32 v7, v10, v11 offset0:128 offset1:160
	ds_write2_b32 v7, v12, v9 offset0:192 offset1:224
	ds_read_b32 v7, v3 offset:224
	v_lshrrev_b32_e32 v10, 1, v48
	v_lshrrev_b32_e32 v11, 1, v49
	v_and_or_b32 v10, v10, 56, s5
	v_and_b32_e32 v11, 0x58, v11
	s_waitcnt lgkmcnt(0)
	v_rcp_f32_e32 v7, v7
	v_lshlrev_b32_e32 v12, 1, v38
	v_mul_f32_e32 v9, v142, v7
	v_mul_f32_e32 v15, v126, v7
	v_mul_f32_e32 v16, v110, v7
	v_mul_f32_e32 v7, v94, v7
	ds_write2_b32 v14, v9, v15 offset1:32
	ds_write2_b32 v14, v16, v7 offset0:64 offset1:96
	ds_read_b32 v7, v3 offset:228
	v_mad_i64_i32 v[8:9], s[2:3], v8, s19, v[4:5]
	v_add_u32_e32 v15, 0x3400, v6
	s_waitcnt lgkmcnt(0)
	v_rcp_f32_e32 v16, v7
	v_lshl_add_u64 v[6:7], v[8:9], 0, s[20:21]
	v_add_u32_e32 v8, s66, v10
	v_or_b32_e32 v10, s5, v11
	v_mul_f32_e32 v9, v143, v16
	v_mul_f32_e32 v11, v127, v16
	v_mul_f32_e32 v17, v111, v16
	v_mul_f32_e32 v16, v95, v16
	ds_write2_b32 v14, v9, v11 offset0:128 offset1:160
	ds_write2_b32 v14, v17, v16 offset0:192 offset1:224
	ds_read_b32 v11, v3 offset:232
	v_lshl_add_u64 v[6:7], v[6:7], 0, v[12:13]
	v_mad_i64_i32 v[8:9], s[2:3], v8, s19, v[4:5]
	v_add_co_u32_e32 v6, vcc, s50, v6
	s_waitcnt lgkmcnt(0)
	v_rcp_f32_e32 v11, v11
	v_lshl_add_u64 v[8:9], v[8:9], 0, s[20:21]
	v_addc_co_u32_e32 v7, vcc, 0, v7, vcc
	v_mul_f32_e32 v14, v144, v11
	v_mul_f32_e32 v16, v128, v11
	v_mul_f32_e32 v17, v112, v11
	v_mul_f32_e32 v11, v96, v11
	ds_write2_b32 v15, v14, v16 offset1:32
	ds_write2_b32 v15, v17, v11 offset0:64 offset1:96
	ds_read_b32 v3, v3 offset:236
	v_lshl_add_u64 v[8:9], v[8:9], 0, v[12:13]
	v_add_co_u32_e32 v8, vcc, s50, v8
	v_add_u32_e32 v10, s66, v10
	s_waitcnt lgkmcnt(0)
	v_rcp_f32_e32 v3, v3
	v_addc_co_u32_e32 v9, vcc, 0, v9, vcc
	v_mad_i64_i32 v[10:11], s[2:3], v10, s19, v[4:5]
	v_mul_f32_e32 v14, v145, v3
	v_mul_f32_e32 v16, v129, v3
	v_mul_f32_e32 v17, v113, v3
	v_mul_f32_e32 v3, v97, v3
	ds_write2_b32 v15, v14, v16 offset0:128 offset1:160
	ds_write2_b32 v15, v17, v3 offset0:192 offset1:224
	s_waitcnt lgkmcnt(0)
	v_or_b32_e32 v3, 0xc0, v213
	global_load_dwordx4 v[14:17], v[6:7], off offset:1024
	global_load_dwordx4 v[18:21], v[8:9], off offset:1024
	v_lshrrev_b32_e32 v8, 1, v3
	v_and_b32_e32 v8, 0x78, v8
	v_or_b32_e32 v8, s5, v8
	v_lshl_add_u64 v[6:7], v[10:11], 0, s[20:21]
	v_add_u32_e32 v8, s66, v8
	v_lshl_add_u64 v[6:7], v[6:7], 0, v[12:13]
	v_mad_i64_i32 v[8:9], s[2:3], v8, s19, v[4:5]
	v_add_co_u32_e32 v6, vcc, s50, v6
	v_lshl_add_u64 v[8:9], v[8:9], 0, s[20:21]
	s_nop 0
	v_addc_co_u32_e32 v7, vcc, 0, v7, vcc
	v_lshl_add_u64 v[8:9], v[8:9], 0, v[12:13]
	v_add_co_u32_e32 v8, vcc, s50, v8
	s_nop 1
	v_addc_co_u32_e32 v9, vcc, 0, v9, vcc
	global_load_dwordx4 v[22:25], v[6:7], off offset:1024
	global_load_dwordx4 v[26:29], v[8:9], off offset:1024
	v_lshrrev_b32_e32 v6, 1, v50
	v_and_b32_e32 v6, 0x98, v6
	v_or_b32_e32 v6, s5, v6
	v_lshrrev_b32_e32 v8, 1, v51
	v_add_u32_e32 v6, s66, v6
	v_and_b32_e32 v8, 0xb8, v8
	v_mad_i64_i32 v[6:7], s[2:3], v6, s19, v[4:5]
	v_or_b32_e32 v8, s5, v8
	v_lshl_add_u64 v[6:7], v[6:7], 0, s[20:21]
	v_add_u32_e32 v8, s66, v8
	v_lshl_add_u64 v[6:7], v[6:7], 0, v[12:13]
	v_mad_i64_i32 v[8:9], s[2:3], v8, s19, v[4:5]
	v_add_co_u32_e32 v6, vcc, s50, v6
	v_lshl_add_u64 v[8:9], v[8:9], 0, s[20:21]
	s_nop 0
	v_addc_co_u32_e32 v7, vcc, 0, v7, vcc
	v_lshl_add_u64 v[8:9], v[8:9], 0, v[12:13]
	v_add_co_u32_e32 v8, vcc, s50, v8
	s_nop 1
	v_addc_co_u32_e32 v9, vcc, 0, v9, vcc
	global_load_dwordx4 v[30:33], v[6:7], off offset:1024
	global_load_dwordx4 v[34:37], v[8:9], off offset:1024
	v_lshrrev_b32_e32 v6, 1, v52
	v_and_b32_e32 v6, 0xd8, v6
	v_or_b32_e32 v6, s5, v6
	v_lshrrev_b32_e32 v8, 1, v53
	v_add_u32_e32 v6, s66, v6
	v_and_b32_e32 v8, 0xf8, v8
	v_mad_i64_i32 v[6:7], s[2:3], v6, s19, v[4:5]
	v_or_b32_e32 v8, s5, v8
	v_lshl_add_u64 v[6:7], v[6:7], 0, s[20:21]
	v_add_u32_e32 v8, s66, v8
	v_lshl_add_u64 v[6:7], v[6:7], 0, v[12:13]
	v_mad_i64_i32 v[4:5], s[2:3], v8, s19, v[4:5]
	v_add_co_u32_e32 v6, vcc, s50, v6
	v_lshl_add_u64 v[4:5], v[4:5], 0, s[20:21]
	s_nop 0
	v_addc_co_u32_e32 v7, vcc, 0, v7, vcc
	v_lshl_add_u64 v[4:5], v[4:5], 0, v[12:13]
	v_add_co_u32_e32 v4, vcc, s50, v4
	s_nop 1
	v_addc_co_u32_e32 v5, vcc, 0, v5, vcc
	global_load_dwordx4 v[8:11], v[6:7], off offset:1024
	s_nop 0
	global_load_dwordx4 v[4:7], v[4:5], off offset:1024
	v_lshl_add_u32 v54, v38, 2, s0
	v_lshl_add_u32 v44, v197, 9, v54
	ds_read_b128 v[38:41], v44
	v_lshl_or_b32 v42, v197, 3, s5
	v_mov_b32_e32 v43, v2
	v_lshl_add_u64 v[46:47], v[42:43], 0, s[66:67]
	ds_read_b128 v[42:45], v44 offset:16
	s_waitcnt vmcnt(7)
	v_lshlrev_b32_e32 v55, 16, v14
	v_and_b32_e32 v14, 0xffff0000, v14
	s_waitcnt lgkmcnt(1)
	v_mul_f32_e32 v38, v38, v55
	v_mul_f32_e32 v14, v39, v14
	v_cvt_pk_bf16_f32 v14, v38, v14
	v_lshlrev_b32_e32 v38, 16, v15
	v_and_b32_e32 v15, 0xffff0000, v15
	v_mul_f32_e32 v38, v40, v38
	v_mul_f32_e32 v15, v41, v15
	v_cvt_pk_bf16_f32 v15, v38, v15
	v_lshlrev_b32_e32 v38, 16, v16
	v_and_b32_e32 v16, 0xffff0000, v16
	s_add_u32 s0, s36, s20
	s_waitcnt lgkmcnt(0)
	v_mul_f32_e32 v38, v42, v38
	v_mul_f32_e32 v16, v43, v16
	s_addc_u32 s1, s37, 0
	v_cvt_pk_bf16_f32 v16, v38, v16
	v_lshlrev_b32_e32 v38, 16, v17
	v_and_b32_e32 v17, 0xffff0000, v17
	v_lshl_add_u64 v[12:13], s[0:1], 0, v[12:13]
	s_mov_b64 s[0:1], 0xc600000
	v_mul_f32_e32 v38, v44, v38
	v_mul_f32_e32 v17, v45, v17
	v_lshl_add_u64 v[12:13], v[12:13], 0, s[0:1]
	v_cvt_pk_bf16_f32 v17, v38, v17
	v_lshlrev_b64 v[38:39], 12, v[46:47]
	v_lshl_add_u64 v[38:39], v[12:13], 0, v[38:39]
	global_store_dwordx4 v[38:39], v[14:17], off
	v_mov_b32_e32 v39, v2
	s_waitcnt vmcnt(7)
	v_lshlrev_b32_e32 v44, 16, v18
	v_lshrrev_b32_e32 v14, 4, v48
	v_lshl_add_u32 v40, v14, 9, v54
	v_lshl_or_b32 v38, v14, 3, s5
	ds_read_b128 v[14:17], v40
	v_and_b32_e32 v18, 0xffff0000, v18
	v_lshl_add_u64 v[42:43], v[38:39], 0, s[66:67]
	ds_read_b128 v[38:41], v40 offset:16
	v_lshrrev_b32_e32 v3, 4, v3
	s_waitcnt lgkmcnt(1)
	v_mul_f32_e32 v14, v14, v44
	v_mul_f32_e32 v15, v15, v18
	v_cvt_pk_bf16_f32 v14, v14, v15
	v_lshlrev_b32_e32 v15, 16, v19
	v_mul_f32_e32 v15, v16, v15
	v_and_b32_e32 v16, 0xffff0000, v19
	v_mul_f32_e32 v16, v17, v16
	v_cvt_pk_bf16_f32 v15, v15, v16
	v_lshlrev_b32_e32 v16, 16, v20
	v_and_b32_e32 v17, 0xffff0000, v20
	s_waitcnt lgkmcnt(0)
	v_mul_f32_e32 v16, v38, v16
	v_mul_f32_e32 v17, v39, v17
	v_cvt_pk_bf16_f32 v16, v16, v17
	v_lshlrev_b32_e32 v17, 16, v21
	v_and_b32_e32 v18, 0xffff0000, v21
	v_mul_f32_e32 v17, v40, v17
	v_mul_f32_e32 v18, v41, v18
	v_cvt_pk_bf16_f32 v17, v17, v18
	v_lshlrev_b64 v[18:19], 12, v[42:43]
	v_lshl_add_u64 v[18:19], v[12:13], 0, v[18:19]
	global_store_dwordx4 v[18:19], v[14:17], off
	v_mov_b32_e32 v19, v2
	s_waitcnt vmcnt(7)
	v_lshlrev_b32_e32 v40, 16, v22
	v_lshrrev_b32_e32 v14, 4, v49
	v_lshl_add_u32 v20, v14, 9, v54
	v_lshl_or_b32 v18, v14, 3, s5
	ds_read_b128 v[14:17], v20
	v_and_b32_e32 v22, 0xffff0000, v22
	v_lshl_add_u64 v[38:39], v[18:19], 0, s[66:67]
	ds_read_b128 v[18:21], v20 offset:16
	s_movk_i32 s6, 0x4000
	s_waitcnt lgkmcnt(1)
	v_mul_f32_e32 v14, v14, v40
	v_mul_f32_e32 v15, v15, v22
	v_cvt_pk_bf16_f32 v14, v14, v15
	v_lshlrev_b32_e32 v15, 16, v23
	v_mul_f32_e32 v15, v16, v15
	v_and_b32_e32 v16, 0xffff0000, v23
	v_mul_f32_e32 v16, v17, v16
	v_cvt_pk_bf16_f32 v15, v15, v16
	v_lshlrev_b32_e32 v16, 16, v24
	v_and_b32_e32 v17, 0xffff0000, v24
	s_waitcnt lgkmcnt(0)
	v_mul_f32_e32 v16, v18, v16
	v_mul_f32_e32 v17, v19, v17
	v_cvt_pk_bf16_f32 v16, v16, v17
	v_lshlrev_b32_e32 v17, 16, v25
	v_and_b32_e32 v18, 0xffff0000, v25
	v_mul_f32_e32 v17, v20, v17
	v_mul_f32_e32 v18, v21, v18
	v_cvt_pk_bf16_f32 v17, v17, v18
	v_lshlrev_b64 v[18:19], 12, v[38:39]
	v_lshl_add_u64 v[18:19], v[12:13], 0, v[18:19]
	global_store_dwordx4 v[18:19], v[14:17], off
	v_lshl_or_b32 v18, v3, 3, s5
	v_lshl_add_u32 v3, v3, 9, v54
	ds_read_b128 v[14:17], v3
	v_mov_b32_e32 v19, v2
	v_lshl_add_u64 v[22:23], v[18:19], 0, s[66:67]
	ds_read_b128 v[18:21], v3 offset:16
	s_waitcnt vmcnt(7)
	v_lshlrev_b32_e32 v3, 16, v26
	s_waitcnt lgkmcnt(1)
	v_mul_f32_e32 v3, v14, v3
	v_and_b32_e32 v14, 0xffff0000, v26
	v_mul_f32_e32 v14, v15, v14
	v_cvt_pk_bf16_f32 v14, v3, v14
	v_lshlrev_b32_e32 v3, 16, v27
	v_and_b32_e32 v15, 0xffff0000, v27
	v_mul_f32_e32 v3, v16, v3
	v_mul_f32_e32 v15, v17, v15
	v_cvt_pk_bf16_f32 v15, v3, v15
	v_lshlrev_b32_e32 v3, 16, v28
	v_and_b32_e32 v16, 0xffff0000, v28
	s_waitcnt lgkmcnt(0)
	v_mul_f32_e32 v3, v18, v3
	v_mul_f32_e32 v16, v19, v16
	v_cvt_pk_bf16_f32 v16, v3, v16
	v_lshlrev_b32_e32 v3, 16, v29
	v_and_b32_e32 v17, 0xffff0000, v29
	v_mul_f32_e32 v3, v20, v3
	v_mul_f32_e32 v17, v21, v17
	v_lshlrev_b64 v[18:19], 12, v[22:23]
	v_cvt_pk_bf16_f32 v17, v3, v17
	v_lshl_add_u64 v[18:19], v[12:13], 0, v[18:19]
	v_lshrrev_b32_e32 v3, 4, v50
	global_store_dwordx4 v[18:19], v[14:17], off
	v_lshl_or_b32 v18, v3, 3, s5
	v_lshl_add_u32 v3, v3, 9, v54
	ds_read_b128 v[14:17], v3
	v_mov_b32_e32 v19, v2
	v_lshl_add_u64 v[22:23], v[18:19], 0, s[66:67]
	ds_read_b128 v[18:21], v3 offset:16
	s_waitcnt vmcnt(7)
	v_lshlrev_b32_e32 v3, 16, v30
	s_waitcnt lgkmcnt(1)
	v_mul_f32_e32 v3, v14, v3
	v_and_b32_e32 v14, 0xffff0000, v30
	v_mul_f32_e32 v14, v15, v14
	v_cvt_pk_bf16_f32 v14, v3, v14
	v_lshlrev_b32_e32 v3, 16, v31
	v_and_b32_e32 v15, 0xffff0000, v31
	v_mul_f32_e32 v3, v16, v3
	v_mul_f32_e32 v15, v17, v15
	v_cvt_pk_bf16_f32 v15, v3, v15
	v_lshlrev_b32_e32 v3, 16, v32
	v_and_b32_e32 v16, 0xffff0000, v32
	s_waitcnt lgkmcnt(0)
	v_mul_f32_e32 v3, v18, v3
	v_mul_f32_e32 v16, v19, v16
	v_cvt_pk_bf16_f32 v16, v3, v16
	v_lshlrev_b32_e32 v3, 16, v33
	v_and_b32_e32 v17, 0xffff0000, v33
	v_mul_f32_e32 v3, v20, v3
	v_mul_f32_e32 v17, v21, v17
	v_lshlrev_b64 v[18:19], 12, v[22:23]
	v_cvt_pk_bf16_f32 v17, v3, v17
	v_lshl_add_u64 v[18:19], v[12:13], 0, v[18:19]
	v_lshrrev_b32_e32 v3, 4, v51
	global_store_dwordx4 v[18:19], v[14:17], off
	v_lshl_or_b32 v18, v3, 3, s5
	v_lshl_add_u32 v3, v3, 9, v54
	ds_read_b128 v[14:17], v3
	v_mov_b32_e32 v19, v2
	v_lshl_add_u64 v[22:23], v[18:19], 0, s[66:67]
	ds_read_b128 v[18:21], v3 offset:16
	s_waitcnt vmcnt(7)
	v_lshlrev_b32_e32 v3, 16, v34
	s_waitcnt lgkmcnt(1)
	v_mul_f32_e32 v3, v14, v3
	v_and_b32_e32 v14, 0xffff0000, v34
	v_mul_f32_e32 v14, v15, v14
	v_cvt_pk_bf16_f32 v14, v3, v14
	v_lshlrev_b32_e32 v3, 16, v35
	v_and_b32_e32 v15, 0xffff0000, v35
	v_mul_f32_e32 v3, v16, v3
	v_mul_f32_e32 v15, v17, v15
	v_cvt_pk_bf16_f32 v15, v3, v15
	v_lshlrev_b32_e32 v3, 16, v36
	v_and_b32_e32 v16, 0xffff0000, v36
	s_waitcnt lgkmcnt(0)
	v_mul_f32_e32 v3, v18, v3
	v_mul_f32_e32 v16, v19, v16
	v_cvt_pk_bf16_f32 v16, v3, v16
	v_lshlrev_b32_e32 v3, 16, v37
	v_and_b32_e32 v17, 0xffff0000, v37
	v_mul_f32_e32 v3, v20, v3
	v_mul_f32_e32 v17, v21, v17
	v_lshlrev_b64 v[18:19], 12, v[22:23]
	v_cvt_pk_bf16_f32 v17, v3, v17
	v_lshl_add_u64 v[18:19], v[12:13], 0, v[18:19]
	v_lshrrev_b32_e32 v3, 4, v52
	global_store_dwordx4 v[18:19], v[14:17], off
	v_lshl_or_b32 v18, v3, 3, s5
	v_lshl_add_u32 v3, v3, 9, v54
	ds_read_b128 v[14:17], v3
	v_mov_b32_e32 v19, v2
	v_lshl_add_u64 v[22:23], v[18:19], 0, s[66:67]
	ds_read_b128 v[18:21], v3 offset:16
	s_waitcnt vmcnt(7)
	v_lshlrev_b32_e32 v3, 16, v8
	v_and_b32_e32 v8, 0xffff0000, v8
	s_waitcnt lgkmcnt(1)
	v_mul_f32_e32 v3, v14, v3
	v_mul_f32_e32 v8, v15, v8
	v_cvt_pk_bf16_f32 v8, v3, v8
	v_lshlrev_b32_e32 v3, 16, v9
	v_and_b32_e32 v9, 0xffff0000, v9
	v_mul_f32_e32 v3, v16, v3
	v_mul_f32_e32 v9, v17, v9
	v_cvt_pk_bf16_f32 v9, v3, v9
	v_lshlrev_b32_e32 v3, 16, v10
	v_and_b32_e32 v10, 0xffff0000, v10
	s_waitcnt lgkmcnt(0)
	v_mul_f32_e32 v3, v18, v3
	v_mul_f32_e32 v10, v19, v10
	v_cvt_pk_bf16_f32 v10, v3, v10
	v_lshlrev_b32_e32 v3, 16, v11
	v_and_b32_e32 v11, 0xffff0000, v11
	v_mul_f32_e32 v3, v20, v3
	v_mul_f32_e32 v11, v21, v11
	v_lshlrev_b64 v[14:15], 12, v[22:23]
	v_cvt_pk_bf16_f32 v11, v3, v11
	v_lshl_add_u64 v[14:15], v[12:13], 0, v[14:15]
	v_lshrrev_b32_e32 v3, 4, v53
	global_store_dwordx4 v[14:15], v[8:11], off
	v_lshl_or_b32 v14, v3, 3, s5
	v_lshl_add_u32 v3, v3, 9, v54
	ds_read_b128 v[8:11], v3
	v_mov_b32_e32 v15, v2
	v_lshl_add_u64 v[18:19], v[14:15], 0, s[66:67]
	ds_read_b128 v[14:17], v3 offset:16
	s_waitcnt vmcnt(7)
	v_lshlrev_b32_e32 v3, 16, v4
	v_and_b32_e32 v4, 0xffff0000, v4
	s_waitcnt lgkmcnt(1)
	v_mul_f32_e32 v3, v8, v3
	v_mul_f32_e32 v4, v9, v4
	v_cvt_pk_bf16_f32 v4, v3, v4
	v_lshlrev_b32_e32 v3, 16, v5
	v_and_b32_e32 v5, 0xffff0000, v5
	v_mul_f32_e32 v3, v10, v3
	v_mul_f32_e32 v5, v11, v5
	v_cvt_pk_bf16_f32 v5, v3, v5
	v_lshlrev_b32_e32 v3, 16, v6
	v_and_b32_e32 v6, 0xffff0000, v6
	s_waitcnt lgkmcnt(0)
	v_mul_f32_e32 v3, v14, v3
	v_mul_f32_e32 v6, v15, v6
	v_cvt_pk_bf16_f32 v6, v3, v6
	v_lshlrev_b32_e32 v3, 16, v7
	v_and_b32_e32 v7, 0xffff0000, v7
	v_lshlrev_b64 v[8:9], 12, v[18:19]
	v_mul_f32_e32 v7, v17, v7
	v_lshl_add_u64 v[8:9], v[12:13], 0, v[8:9]
	v_mul_f32_e32 v3, v16, v3
	v_cvt_pk_bf16_f32 v7, v3, v7
	global_store_dwordx4 v[8:9], v[4:7], off
	s_barrier
	s_mov_b64 s[0:1], 0

	.amdhsa_kernel _Z8mega_fwd6Params
		.amdhsa_group_segment_fixed_size 0
		.amdhsa_private_segment_fixed_size 0
		.amdhsa_kernarg_size 400
		.amdhsa_user_sgpr_count 2
		.amdhsa_user_sgpr_dispatch_ptr 0
		.amdhsa_user_sgpr_queue_ptr 0
		.amdhsa_user_sgpr_kernarg_segment_ptr 1
		.amdhsa_user_sgpr_dispatch_id 0
		.amdhsa_user_sgpr_kernarg_preload_length 0
		.amdhsa_user_sgpr_kernarg_preload_offset 0
		.amdhsa_user_sgpr_private_segment_size 0
		.amdhsa_uses_dynamic_stack 0
		.amdhsa_enable_private_segment 0
		.amdhsa_system_sgpr_workgroup_id_x 1
		.amdhsa_system_sgpr_workgroup_id_y 0
		.amdhsa_system_sgpr_workgroup_id_z 0
		.amdhsa_system_sgpr_workgroup_info 0
		.amdhsa_system_vgpr_workitem_id 0
		.amdhsa_next_free_vgpr 252
		.amdhsa_next_free_sgpr 100
		.amdhsa_accum_offset 252
		.amdhsa_reserve_vcc 1
		.amdhsa_float_round_mode_32 0
		.amdhsa_float_round_mode_16_64 0
		.amdhsa_float_denorm_mode_32 3
		.amdhsa_float_denorm_mode_16_64 3
		.amdhsa_dx10_clamp 1
		.amdhsa_ieee_mode 1
		.amdhsa_fp16_overflow 0
		.amdhsa_tg_split 0
		.amdhsa_exception_fp_ieee_invalid_op 0
		.amdhsa_exception_fp_denorm_src 0
		.amdhsa_exception_fp_ieee_div_zero 0
		.amdhsa_exception_fp_ieee_overflow 0
		.amdhsa_exception_fp_ieee_underflow 0
		.amdhsa_exception_fp_ieee_inexact 0
		.amdhsa_exception_int_div_zero 0
	.end_amdhsa_kernel

amdhsa.kernels:
  - .agpr_count:     0
    .args:
      - .offset:         0
        .size:           144
        .value_kind:     by_value
      - .offset:         144
        .size:           4
        .value_kind:     hidden_block_count_x
      - .offset:         148
        .size:           4
        .value_kind:     hidden_block_count_y
      - .offset:         152
        .size:           4
        .value_kind:     hidden_block_count_z
      - .offset:         156
        .size:           2
        .value_kind:     hidden_group_size_x
      - .offset:         158
        .size:           2
        .value_kind:     hidden_group_size_y
      - .offset:         160
        .size:           2
        .value_kind:     hidden_group_size_z
      - .offset:         162
        .size:           2
        .value_kind:     hidden_remainder_x
      - .offset:         164
        .size:           2
        .value_kind:     hidden_remainder_y
      - .offset:         166
        .size:           2
        .value_kind:     hidden_remainder_z
      - .offset:         184
        .size:           8
        .value_kind:     hidden_global_offset_x
      - .offset:         192
        .size:           8
        .value_kind:     hidden_global_offset_y
      - .offset:         200
        .size:           8
        .value_kind:     hidden_global_offset_z
      - .offset:         208
        .size:           2
        .value_kind:     hidden_grid_dims
      - .offset:         264
        .size:           4
        .value_kind:     hidden_dynamic_lds_size
    .group_segment_fixed_size: 0
    .kernarg_segment_align: 8
    .kernarg_segment_size: 400
    .language:       OpenCL C
    .language_version:
      - 2
      - 0
    .max_flat_workgroup_size: 512
    .name:           _Z8mega_fwd6Params
    .private_segment_fixed_size: 0
    .sgpr_count:     106
    .sgpr_spill_count: 57
    .symbol:         _Z8mega_fwd6Params.kd
    .uniform_work_group_size: 1
    .uses_dynamic_stack: false
    .vgpr_count:     252
    .vgpr_spill_count: 0
    .wavefront_size: 64
